# layer-0 mixer: the 256 GDN-chain blocks (which now finish early) take half of the weight-conversion tile jobs that the MLA-side blocks ran alone
# speedup vs baseline: 1.0724x; 1.0043x over previous
; DI void convert_weights(const P& p, int layer, char* smem, int vb, int nvb, int part) {
;     ...
;   for (int job = vb; job < total; job += nvb) {
;     int j = part == 0 ? (job < 3 * nFF ? job : job + 3 * nFF)
;                       : (job < 3 * nFF ? job + 3 * nFF : 6 * nFF + nIn + nQ + nKV + (job - 3 * nFF));
; __global__ void __launch_bounds__(NTHR, 2) mega(P p) {
;     ...
;       if (!split0 || vb < 256)
;         for (int cid = vb; cid < 256; cid += (split0 ? 256 : nvb)) gdn_chain(p, cid, smem);
;       __syncthreads();
;       if (!split0 || vb >= 256) {
;         XcdBarrier& bs = split0 ? xb2 : xb;
;         {
;           GemmDesc g = gemm_simple((const u16*)(ws + OFF_REGB), EVEN_IN, (const u16*)(ws + OFF_WQUP), 384, T, 768);
;           g.o16 = (u16*)(ws + OFF_QB); g.ldo = 768; g.nreal = 768;
;           gemm_auto<EPI_STORE>(g, T, smem, svb, snvb);
;           GemmDesc g2 = gemm_simple((const u16*)(ws + OFF_REGB) + 384, EVEN_IN, (const u16*)(ws + OFF_WKVUP), 256, T, 1024);
;           g2.o16 = (u16*)(ws + OFF_REGA); g2.ldo = 1024; g2.nreal = 1024;
;           gemm_auto<EPI_STORE>(g2, T, smem, svb, snvb);
;         }
;         xcd_barrier(bs);
;         mla_finalize(p, smem, svb, snvb);
;         xcd_barrier(bs);
;         const u16* Q = (const u16*)(ws + OFF_QB);
;         const u16* Kb = (const u16*)(ws + OFF_KB);
;         const u16* KV = (const u16*)(ws + OFF_REGA);
;         for (int it = svb; it < 1024 + 128; it += snvb) {
;           if (it < 1024) {
;             const int b = it >> 7, h = (it >> 4) & 7, qt = it & 15;
;             attn_item<96, false>(Q, 768, h * 96, Kb, 768, h * 96, KV, 1024, h * 128 + 64, b * SEQ + qt * 128, qt * 128,
;                                  LAT + b * CTXL, b * SEQ, 0, 32, 0.f, (u16*)(ws + OFF_QB), 768, h * 96, smem);
;           } else {
;             const int j = it - 1024;
;             const int b = j >> 4, h = (j >> 1) & 7, qt = j & 1;
;             attn_item<96, false>(Q, 768, h * 96, Kb, 768, h * 96, KV, 1024, h * 128 + 64, LAT + b * CTXL + qt * 128, 0,
;                                  LAT + b * CTXL, b * SEQ, 0, 0, 0.f, (u16*)(ws + OFF_QB), 768, h * 96, smem);
;           }
;         }
;         __syncthreads();
;         convert_weights(p, 0, smem, svb, snvb, 1);
;         convert_weights(p, 1, smem, svb, snvb, 0);
.LBB0_1106:
	s_mov_b32 s101, 0
	v_readlane_b32 s0, v220, 45
	v_readlane_b32 s1, v220, 46
	s_andn2_b64 vcc, exec, s[0:1]
	v_readlane_b32 s40, v218, 17
	s_waitcnt vmcnt(63) expcnt(7) lgkmcnt(15)
	s_barrier
	s_cbranch_vccz .LBB0_1112
.LBB0_1107:
	v_readlane_b32 s0, v220, 51
	v_readlane_b32 s1, v220, 52
	s_andn2_b64 vcc, exec, s[0:1]
	v_readlane_b32 s15, v218, 17
	s_lshl_b32 s0, s101, 9
	s_add_i32 s15, s15, s0
	s_cbranch_vccz .LBB0_1156

; DI void convert_weights(const P& p, int layer, char* smem, int vb, int nvb, int part) {
;     ...
;   for (int job = vb; job < total; job += nvb) {
.LBB0_1111:
	s_movk_i32 s0, 0x200
	s_add_i32 s40, s40, s0
	s_cmpk_lt_i32 s40, 0x940
	s_cbranch_scc0 .LBB0_1107

; DI void convert_weights(const P& p, int layer, char* smem, int vb, int nvb, int part) {
;     ...
;   for (int job = vb; job < total; job += nvb) {
; __global__ void __launch_bounds__(NTHR, 2) mega(P p) {
;     ...
;       if (!split0 || vb < 256)
;         for (int cid = vb; cid < 256; cid += (split0 ? 256 : nvb)) gdn_chain(p, cid, smem);
;       __syncthreads();
;       if (!split0 || vb >= 256) {
.Lgdn_conv:
	v_readlane_b32 s40, v218, 17
	s_mov_b32 s101, 1
	s_add_i32 s40, s40, 0x200
	s_branch .LBB0_1112
.LBB0_1155:
	s_movk_i32 s0, 0x200
	s_add_i32 s15, s15, s0
	s_cmpk_gt_i32 s15, 0xa9f
	s_cbranch_scc1 .LBB0_1108
